# v25 plus static s_setprio 1 during the attention V (softmax) segments, 0 during M segments
# speedup vs baseline: 1.0002x; 1.0002x over previous
; #define SBAR() __builtin_amdgcn_sched_barrier(0)
; #define SWAIT() asm volatile("s_waitcnt vmcnt(3)" ::: "memory")
; #define VSEG(j) do { rowmax_adjust(S0, S1, m2, negm, alpha, (j) == 0); RESC(alpha); l_reg = l_reg * alpha + exp_pack(S0, S1, pa0, pa1, pa2, pa3); } while (0)
; template <bool MLA>
; __device__ __forceinline__ void attn_core(const bf16_t* __restrict__ Qb, const bf16_t* __restrict__ Kh, const bf16_t* __restrict__ Vh, int seq, char* lds,
;                                           f32x16 (&o)[Cfg<MLA>::NCB], const int wid  , const int g  ) {
;     ...
;         SBAR(); VSEG(j + 1);
;         SWAIT(); if (j + 3 < NT) SWRITE(((j + 3) % 3) * SHM_K, ((j + 3) & 3) * SHM_V, SO);
;         if (!(MLA && PROBE_NOLOAD)) { const int tn = (j + 5 < NT) ? j + 5 : NT - 1; SLOAD(SO, tn * 64); } SBAR();
;         __syncthreads();
.LBB0_1149:
	s_min_u32 s0, s95, 0x7e
	s_lshl_b32 s0, s0, 16
	s_add_i32 s16, s0, 0x50000
	s_add_u32 s0, s58, s16
	s_addc_u32 s1, s59, 0
	v_fma_f32 v82, v215, v184, v185
	v_fma_f32 v215, v82, v187, v80
	global_load_dwordx4 v[140:143], v200, s[0:1]
	global_load_dwordx4 v[144:147], v202, s[0:1]
	v_lshl_add_u64 v[80:81], v[204:205], 0, s[16:17]
	global_load_dwordx4 v[148:151], v[80:81], off
	s_add_i32 s94, s94, 2
	s_add_i32 s51, s51, 0x8000
	s_cmpk_gt_u32 s95, 0x81
	s_setprio 0
	s_waitcnt lgkmcnt(0)
	s_barrier
	s_cbranch_scc1 .LBB0_1173

; #define SBAR() __builtin_amdgcn_sched_barrier(0)
; __device__ __forceinline__ float max3f(float a, float b, float c) { return __builtin_fmaxf(__builtin_fmaxf(a, b), c); }
; #define VSEG(j) do { rowmax_adjust(S0, S1, m2, negm, alpha, (j) == 0); RESC(alpha); l_reg = l_reg * alpha + exp_pack(S0, S1, pa0, pa1, pa2, pa3); } while (0)
; __device__ __forceinline__ void rowmax_adjust(f32x16& p0, f32x16& p1, float& m2, f32x16& negm, float& alpha, const bool first) {
;     constexpr float THR2 = THR * 1.4426950408889634f;
;     float pmax = max3f(p0[0], p0[1], p0[2]);
; #pragma unroll
;     for (int r = 3; r < 15; r += 2) pmax = max3f(pmax, p0[r], p0[r + 1]);
;     pmax = max3f(pmax, p0[15], p1[0]);
; #pragma unroll
;     for (int r = 1; r < 15; r += 2) pmax = max3f(pmax, p1[r], p1[r + 1]);
;     pmax = fmaxf(pmax, p1[15]);
;     { auto rr = __builtin_amdgcn_permlane32_swap(__float_as_uint(pmax), __float_as_uint(pmax), false, false);
;       pmax = fmaxf(__uint_as_float(rr[0]), __uint_as_float(rr[1])); }
;     if (!first && __builtin_expect(__all(pmax <= THR2), 1)) { alpha = 1.f; }
; template <bool MLA>
; __device__ __forceinline__ void attn_core(const bf16_t* __restrict__ Qb, const bf16_t* __restrict__ Kh, const bf16_t* __restrict__ Vh, int seq, char* lds,
;                                           f32x16 (&o)[Cfg<MLA>::NCB], const int wid  , const int g  ) {
;     ...
;         SBAR(); MSEG(j); SBAR();
;         __syncthreads();
;         SBAR(); VSEG(j);
.Ld1_a_nopv:
	s_waitcnt lgkmcnt(0)
	s_mov_b64 s[0:1], s[72:73]
	s_barrier
	s_setprio 1
	v_max3_f32 v168, v96, v97, v98
	v_max3_f32 v169, v81, v82, v83
	v_max3_f32 v168, v168, v99, v100
	v_max3_f32 v169, v169, v84, v85
	v_max3_f32 v168, v168, v101, v102
	v_max3_f32 v169, v169, v86, v87
	v_max3_f32 v168, v168, v103, v104
	v_max3_f32 v169, v169, v88, v89
	v_max3_f32 v168, v168, v105, v106
	v_max3_f32 v169, v169, v90, v91
	v_max3_f32 v168, v168, v107, v108
	v_max3_f32 v169, v169, v92, v93
	v_max3_f32 v168, v168, v109, v110
	v_max3_f32 v169, v169, v94, v95
	v_max3_f32 v168, v168, v111, v80
	v_max_f32_e32 v168, v168, v169
	v_mov_b32_e32 v169, v168
	s_nop 1
	v_permlane32_swap_b32_e32 v168, v169
	v_max_f32_e32 v168, v168, v169
	v_cmp_ge_f32_e32 vcc, s83, v168
	v_mov_b32_e32 v184, 1.0
	s_cmp_lg_u64 s[0:1], 0
	s_cbranch_scc1 .Lvt0_first
	s_cmp_lg_u64 vcc, exec
	s_cbranch_scc1 .Lvt0_rare
	s_branch .LBB0_1162

; __device__ __forceinline__ float max3f(float a, float b, float c) { return __builtin_fmaxf(__builtin_fmaxf(a, b), c); }
; __device__ __forceinline__ void rowmax_adjust(f32x16& p0, f32x16& p1, float& m2, f32x16& negm, float& alpha, const bool first) {
;     constexpr float THR2 = THR * 1.4426950408889634f;
;     float pmax = max3f(p0[0], p0[1], p0[2]);
; #pragma unroll
;     for (int r = 3; r < 15; r += 2) pmax = max3f(pmax, p0[r], p0[r + 1]);
;     pmax = max3f(pmax, p0[15], p1[0]);
; #pragma unroll
;     for (int r = 1; r < 15; r += 2) pmax = max3f(pmax, p1[r], p1[r + 1]);
;     pmax = fmaxf(pmax, p1[15]);
;     { auto rr = __builtin_amdgcn_permlane32_swap(__float_as_uint(pmax), __float_as_uint(pmax), false, false);
;       pmax = fmaxf(__uint_as_float(rr[0]), __uint_as_float(rr[1])); }
;     if (!first && __builtin_expect(__all(pmax <= THR2), 1)) { alpha = 1.f; }
.LBB0_1164:
	s_min_u32 s0, s95, 0x7f
	s_lshl_b32 s0, s0, 16
	s_add_i32 s16, s0, 0x40000
	s_add_u32 s0, s58, s16
	s_addc_u32 s1, s59, 0
	global_load_dwordx4 v[132:135], v200, s[0:1]
	global_load_dwordx4 v[128:131], v202, s[0:1]
	v_lshl_add_u64 v[80:81], v[204:205], 0, s[16:17]
	global_load_dwordx4 v[136:139], v[80:81], off
	s_setprio 0
	s_waitcnt lgkmcnt(0)
	s_barrier
	s_or_b32 s0, s95, 1
	s_and_b32 s1, s0, 0xff
	s_mulk_i32 s1, 0xab
	s_bfe_u32 s1, s1, 0x70009
	s_mul_i32 s1, s1, 3
	s_sub_i32 s0, s0, s1
	s_and_b32 s0, s0, 0xff
	s_mulk_i32 s0, 0x2400
	v_add_u32_e32 v84, s0, v218
	s_and_b32 s0, s51, 0x8000
	v_add_u32_e32 v187, s0, v217
	ds_read_b128 v[80:83], v84
	ds_read_b128 v[192:195], v84 offset:4608
	ds_read_b128 v[188:191], v84 offset:32
	ds_read_b128 v[196:199], v84 offset:4640
	ds_read_b128 v[220:223], v84 offset:64
	ds_read_b128 v[228:231], v84 offset:4672
	ds_read_b128 v[224:227], v84 offset:96
	ds_read_b128 v[232:235], v84 offset:4704
	ds_read_b64_tr_b16 v[164:165], v187 offset:0
	ds_read_b64_tr_b16 v[166:167], v187 offset:0x800
	ds_read_b64_tr_b16 v[160:161], v187 offset:0x1000
	ds_read_b64_tr_b16 v[162:163], v187 offset:0x1800
	ds_read_b64_tr_b16 v[156:157], v187 offset:0x2000
	ds_read_b64_tr_b16 v[158:159], v187 offset:0x2800
	ds_read_b64_tr_b16 v[152:153], v187 offset:0x3000
	ds_read_b64_tr_b16 v[154:155], v187 offset:0x3800
	s_waitcnt lgkmcnt(15)
	v_mfma_f32_32x32x16_bf16 v[96:111], v[80:83], v[112:115], v[64:79]
	s_waitcnt lgkmcnt(14)
	v_mfma_f32_32x32x16_bf16 v[80:95], v[192:195], v[112:115], v[64:79]
	s_waitcnt lgkmcnt(13)
	v_mfma_f32_32x32x16_bf16 v[96:111], v[188:191], v[116:119], v[96:111]
	s_waitcnt lgkmcnt(12)
	v_mfma_f32_32x32x16_bf16 v[80:95], v[196:199], v[116:119], v[80:95]
	s_waitcnt lgkmcnt(8)
	ds_read_b64_tr_b16 v[188:189], v187 offset:0x200
	ds_read_b64_tr_b16 v[190:191], v187 offset:0xa00
	ds_read_b64_tr_b16 v[192:193], v187 offset:0x1200
	ds_read_b64_tr_b16 v[194:195], v187 offset:0x1a00
	ds_read_b64_tr_b16 v[196:197], v187 offset:0x2200
	ds_read_b64_tr_b16 v[198:199], v187 offset:0x2a00
	ds_read_b64_tr_b16 v[236:237], v187 offset:0x3200
	ds_read_b64_tr_b16 v[238:239], v187 offset:0x3a00
	v_mfma_f32_32x32x16_bf16 v[96:111], v[220:223], v[120:123], v[96:111]
	v_mfma_f32_32x32x16_bf16 v[80:95], v[228:231], v[120:123], v[80:95]
	v_mfma_f32_32x32x16_bf16 v[96:111], v[224:227], v[124:127], v[96:111]
	v_mfma_f32_32x32x16_bf16 v[80:95], v[232:235], v[124:127], v[80:95]
	ds_read_b64_tr_b16 v[220:221], v187 offset:0x600
	ds_read_b64_tr_b16 v[222:223], v187 offset:0xe00
	ds_read_b64_tr_b16 v[224:225], v187 offset:0x1600
	ds_read_b64_tr_b16 v[226:227], v187 offset:0x1e00
	ds_read_b64_tr_b16 v[228:229], v187 offset:0x2600
	ds_read_b64_tr_b16 v[230:231], v187 offset:0x2e00
	ds_read_b64_tr_b16 v[232:233], v187 offset:0x3600
	ds_read_b64_tr_b16 v[234:235], v187 offset:0x3e00
	s_waitcnt lgkmcnt(15)
	v_mfma_f32_32x32x16_bf16 v[48:63], v[180:183], v[164:167], v[48:63]
	v_mfma_f32_32x32x16_bf16 v[48:63], v[176:179], v[160:163], v[48:63]
	v_mfma_f32_32x32x16_bf16 v[48:63], v[172:175], v[156:159], v[48:63]
	v_mfma_f32_32x32x16_bf16 v[48:63], v[168:171], v[152:155], v[48:63]
	ds_read_b64_tr_b16 v[164:165], v187 offset:0x400
	ds_read_b64_tr_b16 v[166:167], v187 offset:0xc00
	ds_read_b64_tr_b16 v[160:161], v187 offset:0x1400
	ds_read_b64_tr_b16 v[162:163], v187 offset:0x1c00
	ds_read_b64_tr_b16 v[156:157], v187 offset:0x2400
	ds_read_b64_tr_b16 v[158:159], v187 offset:0x2c00
	ds_read_b64_tr_b16 v[152:153], v187 offset:0x3400
	ds_read_b64_tr_b16 v[154:155], v187 offset:0x3c00
	s_waitcnt lgkmcnt(15)
	v_mfma_f32_32x32x16_bf16 v[32:47], v[180:183], v[188:191], v[32:47]
	v_mfma_f32_32x32x16_bf16 v[32:47], v[176:179], v[192:195], v[32:47]
	v_mfma_f32_32x32x16_bf16 v[32:47], v[172:175], v[196:199], v[32:47]
	v_mfma_f32_32x32x16_bf16 v[32:47], v[168:171], v[236:239], v[32:47]
	s_waitcnt lgkmcnt(8)
	v_mfma_f32_32x32x16_bf16 v[0:15], v[180:183], v[220:223], v[0:15]
	v_mfma_f32_32x32x16_bf16 v[0:15], v[176:179], v[224:227], v[0:15]
	v_mfma_f32_32x32x16_bf16 v[0:15], v[172:175], v[228:231], v[0:15]
	v_mfma_f32_32x32x16_bf16 v[0:15], v[168:171], v[232:235], v[0:15]
	s_waitcnt lgkmcnt(0)
	v_mfma_f32_32x32x16_bf16 v[16:31], v[180:183], v[164:167], v[16:31]
	v_mfma_f32_32x32x16_bf16 v[16:31], v[176:179], v[160:163], v[16:31]
	v_mfma_f32_32x32x16_bf16 v[16:31], v[172:175], v[156:159], v[16:31]
	v_mfma_f32_32x32x16_bf16 v[16:31], v[168:171], v[152:155], v[16:31]
	s_barrier
	s_setprio 1
	v_max3_f32 v168, v96, v97, v98
	v_max3_f32 v169, v81, v82, v83
	v_max3_f32 v168, v168, v99, v100
	v_max3_f32 v169, v169, v84, v85
	v_max3_f32 v168, v168, v101, v102
	v_max3_f32 v169, v169, v86, v87
	v_max3_f32 v168, v168, v103, v104
	v_max3_f32 v169, v169, v88, v89
	v_max3_f32 v168, v168, v105, v106
	v_max3_f32 v169, v169, v90, v91
	v_max3_f32 v168, v168, v107, v108
	v_max3_f32 v169, v169, v92, v93
	v_max3_f32 v168, v168, v109, v110
	v_max3_f32 v169, v169, v94, v95
	v_max3_f32 v168, v168, v111, v80
	v_max_f32_e32 v168, v168, v169
	v_mov_b32_e32 v169, v168
	s_nop 1
	v_permlane32_swap_b32_e32 v168, v169
	v_max_f32_e32 v168, v168, v169
	v_cmp_ge_f32_e32 vcc, s83, v168
	v_mov_b32_e32 v187, 1.0
	s_cmp_eq_u64 vcc, exec
	s_cbranch_scc1 .LBB0_1169
	s_branch .LBB0_1171

; #define SBAR() __builtin_amdgcn_sched_barrier(0)
; #define SWAIT() asm volatile("s_waitcnt vmcnt(3)" ::: "memory")
; #define VSEG(j) do { rowmax_adjust(S0, S1, m2, negm, alpha, (j) == 0); RESC(alpha); l_reg = l_reg * alpha + exp_pack(S0, S1, pa0, pa1, pa2, pa3); } while (0)
; template <bool MLA>
; __device__ __forceinline__ void attn_core(const bf16_t* __restrict__ Qb, const bf16_t* __restrict__ Kh, const bf16_t* __restrict__ Vh, int seq, char* lds,
;                                           f32x16 (&o)[Cfg<MLA>::NCB], const int wid  , const int g  ) {
;     ...
;         SBAR(); VSEG(j + 1);
;         SWAIT(); if (j + 3 < NT) SWRITE(((j + 3) % 3) * SHM_K, ((j + 3) & 3) * SHM_V, SO);
;         if (!(MLA && PROBE_NOLOAD)) { const int tn = (j + 5 < NT) ? j + 5 : NT - 1; SLOAD(SO, tn * 64); } SBAR();
;         __syncthreads();
.LBB0_1180:
	s_min_u32 s0, s64, 0x7e
	s_lshl_b32 s0, s0, 16
	s_add_i32 s16, s0, 0x50000
	s_add_u32 s0, s58, s16
	s_addc_u32 s1, s59, 0
	v_fma_f32 v82, v215, v184, v185
	v_fma_f32 v215, v82, v187, v80
	global_load_dwordx4 v[140:143], v200, s[0:1]
	global_load_dwordx4 v[144:147], v202, s[0:1]
	v_lshl_add_u64 v[80:81], v[204:205], 0, s[16:17]
	global_load_dwordx4 v[148:151], v[80:81], off
	s_add_i32 s7, s7, 2
	s_add_i32 s51, s51, 0x8000
	s_cmpk_gt_u32 s64, 0x81
	s_setprio 0
	s_waitcnt lgkmcnt(0)
	s_barrier
	s_cbranch_scc1 .LBB0_1204

; __device__ __forceinline__ float max3f(float a, float b, float c) { return __builtin_fmaxf(__builtin_fmaxf(a, b), c); }
; __device__ __forceinline__ void rowmax_adjust(f32x16& p0, f32x16& p1, float& m2, f32x16& negm, float& alpha, const bool first) {
;     constexpr float THR2 = THR * 1.4426950408889634f;
;     float pmax = max3f(p0[0], p0[1], p0[2]);
; #pragma unroll
;     for (int r = 3; r < 15; r += 2) pmax = max3f(pmax, p0[r], p0[r + 1]);
;     pmax = max3f(pmax, p0[15], p1[0]);
; #pragma unroll
;     for (int r = 1; r < 15; r += 2) pmax = max3f(pmax, p1[r], p1[r + 1]);
;     pmax = fmaxf(pmax, p1[15]);
;     { auto rr = __builtin_amdgcn_permlane32_swap(__float_as_uint(pmax), __float_as_uint(pmax), false, false);
;       pmax = fmaxf(__uint_as_float(rr[0]), __uint_as_float(rr[1])); }
;     if (!first && __builtin_expect(__all(pmax <= THR2), 1)) { alpha = 1.f; }
.Ld1_b_nopv:
	s_waitcnt lgkmcnt(0)
	s_mov_b64 s[0:1], s[60:61]
	s_barrier
	s_setprio 1
	v_max3_f32 v168, v96, v97, v98
	v_max3_f32 v169, v81, v82, v83
	v_max3_f32 v168, v168, v99, v100
	v_max3_f32 v169, v169, v84, v85
	v_max3_f32 v168, v168, v101, v102
	v_max3_f32 v169, v169, v86, v87
	v_max3_f32 v168, v168, v103, v104
	v_max3_f32 v169, v169, v88, v89
	v_max3_f32 v168, v168, v105, v106
	v_max3_f32 v169, v169, v90, v91
	v_max3_f32 v168, v168, v107, v108
	v_max3_f32 v169, v169, v92, v93
	v_max3_f32 v168, v168, v109, v110
	v_max3_f32 v169, v169, v94, v95
	v_max3_f32 v168, v168, v111, v80
	v_max_f32_e32 v168, v168, v169
	v_mov_b32_e32 v169, v168
	s_nop 1
	v_permlane32_swap_b32_e32 v168, v169
	v_max_f32_e32 v168, v168, v169
	v_cmp_ge_f32_e32 vcc, s83, v168
	v_mov_b32_e32 v184, 1.0
	s_cmp_lg_u64 s[0:1], 0
	s_cbranch_scc1 .Lvt31_first
	s_cmp_lg_u64 vcc, exec
	s_cbranch_scc1 .Lvt31_rare
	s_branch .LBB0_1193

; __device__ __forceinline__ float max3f(float a, float b, float c) { return __builtin_fmaxf(__builtin_fmaxf(a, b), c); }
; __device__ __forceinline__ void rowmax_adjust(f32x16& p0, f32x16& p1, float& m2, f32x16& negm, float& alpha, const bool first) {
;     constexpr float THR2 = THR * 1.4426950408889634f;
;     float pmax = max3f(p0[0], p0[1], p0[2]);
; #pragma unroll
;     for (int r = 3; r < 15; r += 2) pmax = max3f(pmax, p0[r], p0[r + 1]);
;     pmax = max3f(pmax, p0[15], p1[0]);
; #pragma unroll
;     for (int r = 1; r < 15; r += 2) pmax = max3f(pmax, p1[r], p1[r + 1]);
;     pmax = fmaxf(pmax, p1[15]);
;     { auto rr = __builtin_amdgcn_permlane32_swap(__float_as_uint(pmax), __float_as_uint(pmax), false, false);
;       pmax = fmaxf(__uint_as_float(rr[0]), __uint_as_float(rr[1])); }
;     if (!first && __builtin_expect(__all(pmax <= THR2), 1)) { alpha = 1.f; }
.LBB0_1195:
	s_min_u32 s0, s64, 0x7f
	s_lshl_b32 s0, s0, 16
	s_add_i32 s16, s0, 0x40000
	s_add_u32 s0, s58, s16
	s_addc_u32 s1, s59, 0
	global_load_dwordx4 v[132:135], v200, s[0:1]
	global_load_dwordx4 v[128:131], v202, s[0:1]
	v_lshl_add_u64 v[80:81], v[204:205], 0, s[16:17]
	global_load_dwordx4 v[136:139], v[80:81], off
	s_setprio 0
	s_waitcnt lgkmcnt(0)
	s_barrier
	s_or_b32 s0, s64, 1
	s_and_b32 s1, s0, 0xff
	s_mulk_i32 s1, 0xab
	s_bfe_u32 s1, s1, 0x70009
	s_mul_i32 s1, s1, 3
	s_sub_i32 s0, s0, s1
	s_and_b32 s0, s0, 0xff
	s_mulk_i32 s0, 0x2400
	v_add_u32_e32 v84, s0, v218
	s_and_b32 s0, s51, 0x8000
	v_add_u32_e32 v187, s0, v217
	ds_read_b128 v[80:83], v84
	ds_read_b128 v[192:195], v84 offset:4608
	ds_read_b128 v[188:191], v84 offset:32
	ds_read_b128 v[196:199], v84 offset:4640
	ds_read_b128 v[220:223], v84 offset:64
	ds_read_b128 v[228:231], v84 offset:4672
	ds_read_b128 v[224:227], v84 offset:96
	ds_read_b128 v[232:235], v84 offset:4704
	ds_read_b64_tr_b16 v[164:165], v187 offset:0
	ds_read_b64_tr_b16 v[166:167], v187 offset:0x800
	ds_read_b64_tr_b16 v[160:161], v187 offset:0x1000
	ds_read_b64_tr_b16 v[162:163], v187 offset:0x1800
	ds_read_b64_tr_b16 v[156:157], v187 offset:0x2000
	ds_read_b64_tr_b16 v[158:159], v187 offset:0x2800
	ds_read_b64_tr_b16 v[152:153], v187 offset:0x3000
	ds_read_b64_tr_b16 v[154:155], v187 offset:0x3800
	s_waitcnt lgkmcnt(15)
	v_mfma_f32_32x32x16_bf16 v[96:111], v[80:83], v[112:115], v[64:79]
	s_waitcnt lgkmcnt(14)
	v_mfma_f32_32x32x16_bf16 v[80:95], v[192:195], v[112:115], v[64:79]
	s_waitcnt lgkmcnt(13)
	v_mfma_f32_32x32x16_bf16 v[96:111], v[188:191], v[116:119], v[96:111]
	s_waitcnt lgkmcnt(12)
	v_mfma_f32_32x32x16_bf16 v[80:95], v[196:199], v[116:119], v[80:95]
	s_waitcnt lgkmcnt(8)
	ds_read_b64_tr_b16 v[188:189], v187 offset:0x200
	ds_read_b64_tr_b16 v[190:191], v187 offset:0xa00
	ds_read_b64_tr_b16 v[192:193], v187 offset:0x1200
	ds_read_b64_tr_b16 v[194:195], v187 offset:0x1a00
	ds_read_b64_tr_b16 v[196:197], v187 offset:0x2200
	ds_read_b64_tr_b16 v[198:199], v187 offset:0x2a00
	ds_read_b64_tr_b16 v[236:237], v187 offset:0x3200
	ds_read_b64_tr_b16 v[238:239], v187 offset:0x3a00
	v_mfma_f32_32x32x16_bf16 v[96:111], v[220:223], v[120:123], v[96:111]
	v_mfma_f32_32x32x16_bf16 v[80:95], v[228:231], v[120:123], v[80:95]
	v_mfma_f32_32x32x16_bf16 v[96:111], v[224:227], v[124:127], v[96:111]
	v_mfma_f32_32x32x16_bf16 v[80:95], v[232:235], v[124:127], v[80:95]
	ds_read_b64_tr_b16 v[220:221], v187 offset:0x600
	ds_read_b64_tr_b16 v[222:223], v187 offset:0xe00
	ds_read_b64_tr_b16 v[224:225], v187 offset:0x1600
	ds_read_b64_tr_b16 v[226:227], v187 offset:0x1e00
	ds_read_b64_tr_b16 v[228:229], v187 offset:0x2600
	ds_read_b64_tr_b16 v[230:231], v187 offset:0x2e00
	ds_read_b64_tr_b16 v[232:233], v187 offset:0x3600
	ds_read_b64_tr_b16 v[234:235], v187 offset:0x3e00
	s_waitcnt lgkmcnt(15)
	v_mfma_f32_32x32x16_bf16 v[48:63], v[180:183], v[164:167], v[48:63]
	v_mfma_f32_32x32x16_bf16 v[48:63], v[176:179], v[160:163], v[48:63]
	v_mfma_f32_32x32x16_bf16 v[48:63], v[172:175], v[156:159], v[48:63]
	v_mfma_f32_32x32x16_bf16 v[48:63], v[168:171], v[152:155], v[48:63]
	ds_read_b64_tr_b16 v[164:165], v187 offset:0x400
	ds_read_b64_tr_b16 v[166:167], v187 offset:0xc00
	ds_read_b64_tr_b16 v[160:161], v187 offset:0x1400
	ds_read_b64_tr_b16 v[162:163], v187 offset:0x1c00
	ds_read_b64_tr_b16 v[156:157], v187 offset:0x2400
	ds_read_b64_tr_b16 v[158:159], v187 offset:0x2c00
	ds_read_b64_tr_b16 v[152:153], v187 offset:0x3400
	ds_read_b64_tr_b16 v[154:155], v187 offset:0x3c00
	s_waitcnt lgkmcnt(15)
	v_mfma_f32_32x32x16_bf16 v[32:47], v[180:183], v[188:191], v[32:47]
	v_mfma_f32_32x32x16_bf16 v[32:47], v[176:179], v[192:195], v[32:47]
	v_mfma_f32_32x32x16_bf16 v[32:47], v[172:175], v[196:199], v[32:47]
	v_mfma_f32_32x32x16_bf16 v[32:47], v[168:171], v[236:239], v[32:47]
	s_waitcnt lgkmcnt(8)
	v_mfma_f32_32x32x16_bf16 v[0:15], v[180:183], v[220:223], v[0:15]
	v_mfma_f32_32x32x16_bf16 v[0:15], v[176:179], v[224:227], v[0:15]
	v_mfma_f32_32x32x16_bf16 v[0:15], v[172:175], v[228:231], v[0:15]
	v_mfma_f32_32x32x16_bf16 v[0:15], v[168:171], v[232:235], v[0:15]
	s_waitcnt lgkmcnt(0)
	v_mfma_f32_32x32x16_bf16 v[16:31], v[180:183], v[164:167], v[16:31]
	v_mfma_f32_32x32x16_bf16 v[16:31], v[176:179], v[160:163], v[16:31]
	v_mfma_f32_32x32x16_bf16 v[16:31], v[172:175], v[156:159], v[16:31]
	v_mfma_f32_32x32x16_bf16 v[16:31], v[168:171], v[152:155], v[16:31]
	s_barrier
	s_setprio 1
	v_max3_f32 v168, v96, v97, v98
	v_max3_f32 v169, v81, v82, v83
	v_max3_f32 v168, v168, v99, v100
	v_max3_f32 v169, v169, v84, v85
	v_max3_f32 v168, v168, v101, v102
	v_max3_f32 v169, v169, v86, v87
	v_max3_f32 v168, v168, v103, v104
	v_max3_f32 v169, v169, v88, v89
	v_max3_f32 v168, v168, v105, v106
	v_max3_f32 v169, v169, v90, v91
	v_max3_f32 v168, v168, v107, v108
	v_max3_f32 v169, v169, v92, v93
	v_max3_f32 v168, v168, v109, v110
	v_max3_f32 v169, v169, v94, v95
	v_max3_f32 v168, v168, v111, v80
	v_max_f32_e32 v168, v168, v169
	v_mov_b32_e32 v169, v168
	s_nop 1
	v_permlane32_swap_b32_e32 v168, v169
	v_max_f32_e32 v168, v168, v169
	v_cmp_ge_f32_e32 vcc, s83, v168
	v_mov_b32_e32 v187, 1.0
	s_cmp_eq_u64 vcc, exec
	s_cbranch_scc1 .LBB0_1200
	s_branch .LBB0_1202

; #define SBAR() __builtin_amdgcn_sched_barrier(0)
; #define SWAIT() asm volatile("s_waitcnt vmcnt(3)" ::: "memory")
; #define VSEG(j) do { rowmax_adjust(S0, S1, m2, negm, alpha, (j) == 0); RESC(alpha); l_reg = l_reg * alpha + exp_pack(S0, S1, pa0, pa1, pa2, pa3); } while (0)
; template <bool MLA>
; __device__ __forceinline__ void attn_core(const bf16_t* __restrict__ Qb, const bf16_t* __restrict__ Kh, const bf16_t* __restrict__ Vh, int seq, char* lds,
;                                           f32x16 (&o)[Cfg<MLA>::NCB], const int wid  , const int g  ) {
;     ...
;         if (!(MLA && PROBE_NOLOAD)) { const int tn = (j + 4 < NT) ? j + 4 : NT - 1; SLOAD(SE, tn * 64); } SBAR();
;         __syncthreads();
;         SBAR(); MSEG(j + 1); SBAR();
;         __syncthreads();
;         SBAR(); VSEG(j + 1);
;         SWAIT(); if (j + 3 < NT) SWRITE(((j + 3) % 3) * SHM_K, ((j + 3) & 3) * SHM_V, SO);
;         if (!(MLA && PROBE_NOLOAD)) { const int tn = (j + 5 < NT) ? j + 5 : NT - 1; SLOAD(SO, tn * 64); } SBAR();
;         __syncthreads();
.LBB0_1227:
	s_min_u32 s10, s61, 0x7e
	s_lshl_b32 s10, s10, 6
	s_add_i32 s16, s10, 0x140
	s_mul_i32 s10, s16, 0x600
	s_add_u32 s10, s58, s10
	s_addc_u32 s11, s59, 0
	s_lshl_b32 s16, s16, 10
	v_fma_f32 v50, v157, v158, v159
	v_fma_f32 v157, v50, v161, v48
	v_lshl_add_u64 v[48:49], v[148:149], 0, s[16:17]
	global_load_dwordx4 v[116:119], v[48:49], off
	global_load_dwordx4 v[124:127], v146, s[10:11]
	global_load_dwordx4 v[120:123], v200, s[10:11]
	s_add_i32 s51, s51, 2
	s_addk_i32 s60, 0x4000
	s_cmpk_gt_u32 s61, 0x81
	s_setprio 0
	s_waitcnt lgkmcnt(0)
	s_barrier
	s_cbranch_scc1 .LBB0_1246
.LBB0_1228:
	s_add_i32 s61, s51, -3
	s_mul_i32 s10, s61, 0xab
	s_bfe_u32 s10, s10, 0x70009
	s_mul_i32 s10, s10, 3
	s_sub_i32 s10, s61, s10
	s_and_b32 s10, s10, 0xff
	s_mulk_i32 s10, 0x4400
	v_add_u32_e32 v52, s10, v152
	ds_read_b128 v[48:51], v52 offset:32768
	ds_read_b128 v[158:161], v52 offset:32800
	ds_read_b128 v[162:165], v52 offset:41472
	ds_read_b128 v[166:169], v52 offset:41504
	ds_read_b128 v[170:173], v52 offset:32832
	ds_read_b128 v[174:177], v52 offset:32864
	ds_read_b128 v[178:181], v52 offset:41536
	ds_read_b128 v[182:185], v52 offset:41568
	ds_read_b128 v[186:189], v52 offset:32896
	ds_read_b128 v[190:193], v52 offset:32928
	ds_read_b128 v[194:197], v52 offset:41600
	ds_read_b128 v[202:205], v52 offset:41632
	s_waitcnt lgkmcnt(11)
	v_mfma_f32_32x32x16_bf16 v[64:79], v[48:51], v[80:83], v[32:47]
	s_waitcnt lgkmcnt(9)
	v_mfma_f32_32x32x16_bf16 v[48:63], v[162:165], v[80:83], v[32:47]
	v_mfma_f32_32x32x16_bf16 v[64:79], v[158:161], v[84:87], v[64:79]
	s_waitcnt lgkmcnt(8)
	v_mfma_f32_32x32x16_bf16 v[48:63], v[166:169], v[84:87], v[48:63]
	s_waitcnt lgkmcnt(7)
	v_mfma_f32_32x32x16_bf16 v[64:79], v[170:173], v[88:91], v[64:79]
	s_waitcnt lgkmcnt(5)
	v_mfma_f32_32x32x16_bf16 v[48:63], v[178:181], v[88:91], v[48:63]
	s_waitcnt lgkmcnt(4)
	s_waitcnt lgkmcnt(3)
	s_waitcnt lgkmcnt(1)
	s_waitcnt lgkmcnt(0)
	s_and_b32 s62, s60, 0x6000
	v_add_u32_e32 v198, s62, v155
	ds_read_b64_tr_b16 v[158:159], v198 offset:0
	ds_read_b64_tr_b16 v[160:161], v198 offset:0x400
	ds_read_b64_tr_b16 v[162:163], v198 offset:0x800
	ds_read_b64_tr_b16 v[164:165], v198 offset:0xc00
	ds_read_b64_tr_b16 v[166:167], v198 offset:0x1000
	ds_read_b64_tr_b16 v[168:169], v198 offset:0x1400
	ds_read_b64_tr_b16 v[170:171], v198 offset:0x1800
	ds_read_b64_tr_b16 v[172:173], v198 offset:0x1c00
	ds_read_b64_tr_b16 v[178:179], v198 offset:0x200
	ds_read_b64_tr_b16 v[180:181], v198 offset:0x600
	ds_read_b64_tr_b16 v[210:211], v198 offset:0xa00
	ds_read_b64_tr_b16 v[212:213], v198 offset:0xe00
	ds_read_b64_tr_b16 v[214:215], v198 offset:0x1200
	ds_read_b64_tr_b16 v[216:217], v198 offset:0x1600
	ds_read_b64_tr_b16 v[218:219], v198 offset:0x1a00
	ds_read_b64_tr_b16 v[220:221], v198 offset:0x1e00
	s_nop 0
	v_mfma_f32_32x32x16_bf16 v[64:79], v[174:177], v[92:95], v[64:79]
	v_mfma_f32_32x32x16_bf16 v[48:63], v[182:185], v[92:95], v[48:63]
	v_mfma_f32_32x32x16_bf16 v[64:79], v[186:189], v[96:99], v[64:79]
	v_mfma_f32_32x32x16_bf16 v[48:63], v[194:197], v[96:99], v[48:63]
	v_mfma_f32_32x32x16_bf16 v[64:79], v[190:193], v[100:103], v[64:79]
	v_mfma_f32_32x32x16_bf16 v[48:63], v[202:205], v[100:103], v[48:63]
	s_waitcnt lgkmcnt(0)
	v_mfma_f32_32x32x16_bf16 v[0:15], v[140:143], v[158:161], v[0:15]
	v_mfma_f32_32x32x16_bf16 v[16:31], v[140:143], v[178:181], v[16:31]
	v_mfma_f32_32x32x16_bf16 v[0:15], v[136:139], v[162:165], v[0:15]
	v_mfma_f32_32x32x16_bf16 v[16:31], v[136:139], v[210:213], v[16:31]
	v_mfma_f32_32x32x16_bf16 v[0:15], v[132:135], v[166:169], v[0:15]
	v_mfma_f32_32x32x16_bf16 v[16:31], v[132:135], v[214:217], v[16:31]
	v_mfma_f32_32x32x16_bf16 v[0:15], v[128:131], v[170:173], v[0:15]
	v_mfma_f32_32x32x16_bf16 v[16:31], v[128:131], v[218:221], v[16:31]
	s_barrier
	s_setprio 1
	s_nop 1
	v_max3_f32 v128, v64, v65, v66
	v_max3_f32 v129, v49, v50, v51
	v_max3_f32 v128, v128, v67, v68
	v_max3_f32 v129, v129, v52, v53
	v_max3_f32 v128, v128, v69, v70
	v_max3_f32 v129, v129, v54, v55
	v_max3_f32 v128, v128, v71, v72
	v_max3_f32 v129, v129, v56, v57
	v_max3_f32 v128, v128, v73, v74
	v_max3_f32 v129, v129, v58, v59
	v_max3_f32 v128, v128, v75, v76
	v_max3_f32 v129, v129, v60, v61
	v_max3_f32 v128, v128, v77, v78
	v_max3_f32 v129, v129, v62, v63
	v_max3_f32 v128, v128, v79, v48
	v_max_f32_e32 v128, v128, v129
	v_mov_b32_e32 v129, v128
	s_nop 1
	v_permlane32_swap_b32_e32 v128, v129
	v_max_f32_e32 v128, v128, v129
	v_cmp_ge_f32_e32 vcc, s83, v128
	v_mov_b32_e32 v158, 1.0
	s_cmp_eq_u64 vcc, exec
	s_cbranch_scc1 .LBB0_1233
	s_branch .LBB0_1244

; __device__ __forceinline__ float max3f(float a, float b, float c) { return __builtin_fmaxf(__builtin_fmaxf(a, b), c); }
; __device__ __forceinline__ void rowmax_adjust(f32x16& p0, f32x16& p1, float& m2, f32x16& negm, float& alpha, const bool first) {
;     constexpr float THR2 = THR * 1.4426950408889634f;
;     float pmax = max3f(p0[0], p0[1], p0[2]);
; #pragma unroll
;     for (int r = 3; r < 15; r += 2) pmax = max3f(pmax, p0[r], p0[r + 1]);
;     pmax = max3f(pmax, p0[15], p1[0]);
; #pragma unroll
;     for (int r = 1; r < 15; r += 2) pmax = max3f(pmax, p1[r], p1[r + 1]);
;     pmax = fmaxf(pmax, p1[15]);
;     { auto rr = __builtin_amdgcn_permlane32_swap(__float_as_uint(pmax), __float_as_uint(pmax), false, false);
;       pmax = fmaxf(__uint_as_float(rr[0]), __uint_as_float(rr[1])); }
;     if (!first && __builtin_expect(__all(pmax <= THR2), 1)) { alpha = 1.f; }
.LBB0_1236:
	s_min_u32 s10, s61, 0x7f
	s_lshl_b32 s10, s10, 6
	s_add_i32 s16, s10, 0x100
	s_add_i32 s38, s60, 0xffffa000
	s_setprio 0
	s_mul_i32 s10, s16, 0x600
	s_add_u32 s10, s58, s10
	s_addc_u32 s11, s59, 0
	s_lshl_b32 s16, s16, 10
	v_lshl_add_u64 v[48:49], v[148:149], 0, s[16:17]
	global_load_dwordx4 v[112:115], v[48:49], off
	global_load_dwordx4 v[108:111], v146, s[10:11]
	global_load_dwordx4 v[104:107], v200, s[10:11]
	s_waitcnt lgkmcnt(0)
	s_barrier
	s_or_b32 s10, s61, 1
	s_and_b32 s11, s10, 0xff
	s_mulk_i32 s11, 0xab
	s_bfe_u32 s11, s11, 0x70009
	s_mul_i32 s11, s11, 3
	s_sub_i32 s10, s10, s11
	s_and_b32 s10, s10, 0xff
	s_mulk_i32 s10, 0x4400
	v_add_u32_e32 v52, s10, v152
	ds_read_b128 v[48:51], v52 offset:32768
	ds_read_b128 v[162:165], v52 offset:32800
	ds_read_b128 v[166:169], v52 offset:41472
	ds_read_b128 v[170:173], v52 offset:41504
	ds_read_b128 v[174:177], v52 offset:32832
	ds_read_b128 v[178:181], v52 offset:32864
	ds_read_b128 v[182:185], v52 offset:41536
	ds_read_b128 v[186:189], v52 offset:41568
	ds_read_b128 v[190:193], v52 offset:32896
	ds_read_b128 v[194:197], v52 offset:32928
	ds_read_b128 v[202:205], v52 offset:41600
	ds_read_b128 v[210:213], v52 offset:41632
	s_and_b32 s10, s38, 0x4000
	s_waitcnt lgkmcnt(11)
	v_mfma_f32_32x32x16_bf16 v[64:79], v[48:51], v[80:83], v[32:47]
	s_waitcnt lgkmcnt(9)
	v_mfma_f32_32x32x16_bf16 v[48:63], v[166:169], v[80:83], v[32:47]
	v_mfma_f32_32x32x16_bf16 v[64:79], v[162:165], v[84:87], v[64:79]
	s_waitcnt lgkmcnt(8)
	v_mfma_f32_32x32x16_bf16 v[48:63], v[170:173], v[84:87], v[48:63]
	s_waitcnt lgkmcnt(7)
	v_mfma_f32_32x32x16_bf16 v[64:79], v[174:177], v[88:91], v[64:79]
	s_waitcnt lgkmcnt(5)
	v_mfma_f32_32x32x16_bf16 v[48:63], v[182:185], v[88:91], v[48:63]
	v_add_u32_e32 v161, s10, v155
	s_waitcnt lgkmcnt(4)
	s_waitcnt lgkmcnt(3)
	s_waitcnt lgkmcnt(1)
	s_waitcnt lgkmcnt(0)
	ds_read_b64_tr_b16 v[162:163], v161 offset:0
	ds_read_b64_tr_b16 v[164:165], v161 offset:0x400
	ds_read_b64_tr_b16 v[166:167], v161 offset:0x800
	ds_read_b64_tr_b16 v[168:169], v161 offset:0xc00
	ds_read_b64_tr_b16 v[170:171], v161 offset:0x1000
	ds_read_b64_tr_b16 v[172:173], v161 offset:0x1400
	ds_read_b64_tr_b16 v[174:175], v161 offset:0x1800
	ds_read_b64_tr_b16 v[176:177], v161 offset:0x1c00
	ds_read_b64_tr_b16 v[182:183], v161 offset:0x200
	ds_read_b64_tr_b16 v[184:185], v161 offset:0x600
	ds_read_b64_tr_b16 v[214:215], v161 offset:0xa00
	ds_read_b64_tr_b16 v[216:217], v161 offset:0xe00
	ds_read_b64_tr_b16 v[218:219], v161 offset:0x1200
	ds_read_b64_tr_b16 v[220:221], v161 offset:0x1600
	ds_read_b64_tr_b16 v[222:223], v161 offset:0x1a00
	ds_read_b64_tr_b16 v[224:225], v161 offset:0x1e00
	s_nop 0
	v_mfma_f32_32x32x16_bf16 v[64:79], v[178:181], v[92:95], v[64:79]
	v_mfma_f32_32x32x16_bf16 v[48:63], v[186:189], v[92:95], v[48:63]
	v_mfma_f32_32x32x16_bf16 v[64:79], v[190:193], v[96:99], v[64:79]
	v_mfma_f32_32x32x16_bf16 v[48:63], v[202:205], v[96:99], v[48:63]
	v_mfma_f32_32x32x16_bf16 v[64:79], v[194:197], v[100:103], v[64:79]
	v_mfma_f32_32x32x16_bf16 v[48:63], v[210:213], v[100:103], v[48:63]
	s_waitcnt lgkmcnt(0)
	v_mfma_f32_32x32x16_bf16 v[0:15], v[140:143], v[162:165], v[0:15]
	v_mfma_f32_32x32x16_bf16 v[16:31], v[140:143], v[182:185], v[16:31]
	v_mfma_f32_32x32x16_bf16 v[0:15], v[136:139], v[166:169], v[0:15]
	v_mfma_f32_32x32x16_bf16 v[16:31], v[136:139], v[214:217], v[16:31]
	v_mfma_f32_32x32x16_bf16 v[0:15], v[132:135], v[170:173], v[0:15]
	v_mfma_f32_32x32x16_bf16 v[16:31], v[132:135], v[218:221], v[16:31]
	v_mfma_f32_32x32x16_bf16 v[0:15], v[128:131], v[174:177], v[0:15]
	v_mfma_f32_32x32x16_bf16 v[16:31], v[128:131], v[222:225], v[16:31]
	s_barrier
	s_setprio 1
	s_nop 1
	v_max3_f32 v128, v64, v65, v66
	v_max3_f32 v129, v49, v50, v51
	v_max3_f32 v128, v128, v67, v68
	v_max3_f32 v129, v129, v52, v53
	v_max3_f32 v128, v128, v69, v70
	v_max3_f32 v129, v129, v54, v55
	v_max3_f32 v128, v128, v71, v72
	v_max3_f32 v129, v129, v56, v57
	v_max3_f32 v128, v128, v73, v74
	v_max3_f32 v129, v129, v58, v59
	v_max3_f32 v128, v128, v75, v76
	v_max3_f32 v129, v129, v60, v61
	v_max3_f32 v128, v128, v77, v78
	v_max3_f32 v129, v129, v62, v63
	v_max3_f32 v128, v128, v79, v48
	v_max_f32_e32 v128, v128, v129
	v_mov_b32_e32 v129, v128
	s_nop 1
	v_permlane32_swap_b32_e32 v128, v129
	v_max_f32_e32 v128, v128, v129
	v_cmp_ge_f32_e32 vcc, s83, v128
	v_mov_b32_e32 v161, 1.0
	s_cmp_eq_u64 vcc, exec
	s_cbranch_scc1 .LBB0_1241
	s_branch .LBB0_1245
